# MoE weight conversion: bank-swizzled the fp8 staging tile in LDS (store_tile's reads had 8 lanes per bank); staging writer and reader base addresses only
# speedup vs baseline: 1.0043x; 1.0043x over previous
.LBB0_796:
	s_lshl_b32 s20, s27, 3
	s_and_b32 s20, s20, s19
	s_lshl_b32 s19, s27, 7
	s_and_b32 s19, s19, 0x780
	s_add_i32 s19, s19, s2
	v_or_b32_e32 v3, s19, v1
	v_mad_u64_u32 v[4:5], s[28:29], s18, v3, 0
	v_lshl_add_u64 v[4:5], v[4:5], 2, s[16:17]
	s_ashr_i32 s21, s20, 31
	v_lshl_add_u64 v[4:5], s[20:21], 2, v[4:5]
	v_mov_b32_e32 v3, 0
	s_add_i32 s29, s3, 0x10000
	s_mov_b32 s17, 0
	v_lshl_add_u64 v[4:5], v[4:5], 0, v[2:3]
	s_mov_b32 m0, s29
	s_lshl_b32 s16, s18, 3
	global_load_lds_dwordx4 v[4:5], off nt
	v_lshl_add_u64 v[4:5], v[4:5], 0, s[16:17]
	s_add_i32 m0, s3, 0x10400
	v_or_b32_e32 v8, s2, v1
	global_load_lds_dwordx4 v[4:5], off nt
	v_lshl_add_u64 v[4:5], v[4:5], 0, s[16:17]
	s_add_i32 m0, s3, 0x10800
	v_and_b32_e32 v1, 7, v0
	global_load_lds_dwordx4 v[4:5], off nt
	v_lshl_add_u64 v[4:5], v[4:5], 0, s[16:17]
	s_add_i32 m0, s3, 0x10c00
	v_lshrrev_b32_e32 v6, 3, v0
	global_load_lds_dwordx4 v[4:5], off nt
	v_lshl_add_u64 v[4:5], v[4:5], 0, s[16:17]
	s_add_i32 m0, s3, 0x11000
	v_lshlrev_b32_e32 v7, 11, v1
	global_load_lds_dwordx4 v[4:5], off nt
	v_lshl_add_u64 v[4:5], v[4:5], 0, s[16:17]
	s_add_i32 m0, s3, 0x11400
	v_lshlrev_b32_e32 v9, 3, v210
	global_load_lds_dwordx4 v[4:5], off nt
	v_lshl_add_u64 v[4:5], v[4:5], 0, s[16:17]
	s_add_i32 m0, s3, 0x11800
	v_add_u32_e32 v10, s3, v9
	global_load_lds_dwordx4 v[4:5], off nt
	v_lshl_add_u64 v[4:5], v[4:5], 0, s[16:17]
	s_add_i32 m0, s3, 0x11c00
	s_waitcnt lgkmcnt(0)
	s_add_u32 s30, s4, 0x78000000
	global_load_lds_dwordx4 v[4:5], off nt
	s_addc_u32 s31, s5, 0
	s_add_u32 s27, s4, 0x58000000
	v_readlane_b32 s4, v255, 12
	s_addc_u32 s28, s5, 0
	v_lshlrev_b32_e32 v4, 4, v1
	s_add_i32 s2, 0, 0x20000
	v_lshl_add_u32 v1, v1, 3, v6
	v_and_b32_e32 v1, 63, v1
	v_lshlrev_b32_e32 v1, 2, v1
	s_lshl_b32 s4, s4, 11
	v_add3_u32 v7, s2, v7, v1
	s_add_i32 s2, s2, s4
	v_readlane_b32 s4, v255, 3
	v_mov_b32_e32 v5, v3
	v_or_b32_e32 v1, 64, v6
	s_mul_i32 s33, s4, 3
	s_sub_i32 s34, 0, s4
	s_lshl_b32 s35, s4, 1
	v_readlane_b32 s99, v255, 12
	s_movk_i32 s100, 0x100
	s_lshl_b32 s99, s99, 5
	v_add_u32_e32 v11, s99, v9
	v_and_b32_e32 v11, 0xff, v11
	v_and_or_b32 v11, v9, s100, v11
	v_add_u32_e32 v11, s2, v11
	s_mov_b32 s2, s96
	s_mov_b32 s36, 0
	s_branch .LBB0_799

.LBB0_901:
	s_lshl_b32 s18, s25, 3
	s_and_b32 s18, s18, s17
	s_lshl_b32 s17, s25, 7
	s_and_b32 s17, s17, 0x780
	s_add_i32 s17, s17, s2
	v_or_b32_e32 v3, s17, v1
	v_mad_u64_u32 v[4:5], s[26:27], s16, v3, 0
	v_lshl_add_u64 v[4:5], v[4:5], 2, s[12:13]
	s_ashr_i32 s19, s18, 31
	v_lshl_add_u64 v[4:5], s[18:19], 2, v[4:5]
	v_mov_b32_e32 v3, 0
	s_add_i32 s27, s3, 0x10000
	s_mov_b32 s13, 0
	v_lshl_add_u64 v[4:5], v[4:5], 0, v[2:3]
	s_mov_b32 m0, s27
	s_lshl_b32 s12, s16, 3
	global_load_lds_dwordx4 v[4:5], off nt
	v_lshl_add_u64 v[4:5], v[4:5], 0, s[12:13]
	s_add_i32 m0, s3, 0x10400
	v_or_b32_e32 v7, s2, v1
	global_load_lds_dwordx4 v[4:5], off nt
	v_lshl_add_u64 v[4:5], v[4:5], 0, s[12:13]
	s_add_i32 m0, s3, 0x10800
	v_and_b32_e32 v1, 7, v0
	global_load_lds_dwordx4 v[4:5], off nt
	v_lshl_add_u64 v[4:5], v[4:5], 0, s[12:13]
	s_add_i32 m0, s3, 0x10c00
	v_lshlrev_b32_e32 v6, 11, v1
	global_load_lds_dwordx4 v[4:5], off nt
	v_lshl_add_u64 v[4:5], v[4:5], 0, s[12:13]
	s_add_i32 m0, s3, 0x11000
	v_lshlrev_b32_e32 v8, 3, v210
	global_load_lds_dwordx4 v[4:5], off nt
	v_lshl_add_u64 v[4:5], v[4:5], 0, s[12:13]
	s_add_i32 m0, s3, 0x11400
	v_add_u32_e32 v9, s3, v8
	global_load_lds_dwordx4 v[4:5], off nt
	v_lshl_add_u64 v[4:5], v[4:5], 0, s[12:13]
	s_add_i32 m0, s3, 0x11800
	s_mov_b32 s34, 0
	global_load_lds_dwordx4 v[4:5], off nt
	v_lshl_add_u64 v[4:5], v[4:5], 0, s[12:13]
	s_add_i32 m0, s3, 0x11c00
	s_waitcnt lgkmcnt(0)
	s_add_u32 s28, s4, 0x78000000
	global_load_lds_dwordx4 v[4:5], off nt
	s_addc_u32 s29, s5, 0
	s_add_u32 s25, s4, 0x58000000
	v_readlane_b32 s4, v255, 12
	s_addc_u32 s26, s5, 0
	v_lshlrev_b32_e32 v4, 4, v1
	s_add_i32 s2, 0, 0x20000
	v_lshl_add_u32 v1, v1, 3, v186
	v_and_b32_e32 v1, 63, v1
	v_lshlrev_b32_e32 v1, 2, v1
	s_lshl_b32 s4, s4, 11
	v_add3_u32 v6, s2, v6, v1
	s_add_i32 s2, s2, s4
	v_readlane_b32 s4, v255, 3
	v_mov_b32_e32 v5, v3
	v_or_b32_e32 v1, 64, v186
	s_mul_i32 s30, s4, 3
	s_sub_i32 s31, 0, s4
	s_lshl_b32 s33, s4, 1
	v_readlane_b32 s99, v255, 12
	s_movk_i32 s100, 0x100
	s_lshl_b32 s99, s99, 5
	v_add_u32_e32 v10, s99, v8
	v_and_b32_e32 v10, 0xff, v10
	v_and_or_b32 v10, v8, s100, v10
	v_add_u32_e32 v10, s2, v10
	s_mov_b32 s2, s96
	s_branch .LBB0_904
